# w_in GEMM gate-tile epilogue (sigmoid -> bf16, 12 of 19 column tiles) hand-written with packed f32 ops and no hazard nops
# speedup vs baseline: 1.0521x; 1.0084x over previous
.LBB0_1279:
	s_andn2_b64 vcc, exec, s[0:1]
	s_cbranch_vccnz .LBB0_1024
	s_cmp_lt_u32 s42, 7
	s_cbranch_scc1 .Lg0_orig
	v_readlane_b32 s0, v251, 29
	v_readlane_b32 s1, v251, 30
	v_add_u32_e32 v0, s24, v143
	v_lshl_or_b32 v150, s42, 8, v218
	v_mul_u32_u24_e32 v0, 0x1800, v0
	v_add_u32_e32 v150, 0xfffff900, v150
	v_mov_b32_e32 v130, 0xbfb8aa3b
	v_mov_b32_e32 v131, 0xbfb8aa3b
	v_mov_b32_e32 v132, 1.0
	v_mov_b32_e32 v133, 1.0
	v_lshl_add_u32 v150, v150, 1, v0
	v_add_u32_e32 v151, 0x0, v150
	v_pk_mul_f32 v[126:127], v[126:127], v[130:131]
	v_pk_mul_f32 v[128:129], v[128:129], v[130:131]
	v_exp_f32_e32 v126, v126
	v_exp_f32_e32 v127, v127
	v_exp_f32_e32 v128, v128
	v_exp_f32_e32 v129, v129
	v_pk_add_f32 v[126:127], v[126:127], v[132:133]
	v_pk_add_f32 v[128:129], v[128:129], v[132:133]
	v_rcp_f32_e32 v126, v126
	v_rcp_f32_e32 v127, v127
	v_rcp_f32_e32 v128, v128
	v_rcp_f32_e32 v129, v129
	v_cvt_pk_bf16_f32 v126, v126, v127
	v_cvt_pk_bf16_f32 v127, v128, v129
	global_store_dwordx2 v151, v[126:127], s[0:1]
	v_pk_mul_f32 v[122:123], v[122:123], v[130:131]
	v_pk_mul_f32 v[124:125], v[124:125], v[130:131]
	v_exp_f32_e32 v122, v122
	v_exp_f32_e32 v123, v123
	v_exp_f32_e32 v124, v124
	v_exp_f32_e32 v125, v125
	v_pk_add_f32 v[122:123], v[122:123], v[132:133]
	v_pk_add_f32 v[124:125], v[124:125], v[132:133]
	v_rcp_f32_e32 v122, v122
	v_rcp_f32_e32 v123, v123
	v_rcp_f32_e32 v124, v124
	v_rcp_f32_e32 v125, v125
	v_cvt_pk_bf16_f32 v122, v122, v123
	v_cvt_pk_bf16_f32 v123, v124, v125
	global_store_dwordx2 v151, v[122:123], s[0:1] offset:32
	v_pk_mul_f32 v[62:63], v[62:63], v[130:131]
	v_pk_mul_f32 v[64:65], v[64:65], v[130:131]
	v_exp_f32_e32 v62, v62
	v_exp_f32_e32 v63, v63
	v_exp_f32_e32 v64, v64
	v_exp_f32_e32 v65, v65
	v_pk_add_f32 v[62:63], v[62:63], v[132:133]
	v_pk_add_f32 v[64:65], v[64:65], v[132:133]
	v_rcp_f32_e32 v62, v62
	v_rcp_f32_e32 v63, v63
	v_rcp_f32_e32 v64, v64
	v_rcp_f32_e32 v65, v65
	v_cvt_pk_bf16_f32 v62, v62, v63
	v_cvt_pk_bf16_f32 v63, v64, v65
	global_store_dwordx2 v151, v[62:63], s[0:1] offset:256
	v_pk_mul_f32 v[58:59], v[58:59], v[130:131]
	v_pk_mul_f32 v[60:61], v[60:61], v[130:131]
	v_exp_f32_e32 v58, v58
	v_exp_f32_e32 v59, v59
	v_exp_f32_e32 v60, v60
	v_exp_f32_e32 v61, v61
	v_pk_add_f32 v[58:59], v[58:59], v[132:133]
	v_pk_add_f32 v[60:61], v[60:61], v[132:133]
	v_rcp_f32_e32 v58, v58
	v_rcp_f32_e32 v59, v59
	v_rcp_f32_e32 v60, v60
	v_rcp_f32_e32 v61, v61
	v_cvt_pk_bf16_f32 v58, v58, v59
	v_cvt_pk_bf16_f32 v59, v60, v61
	global_store_dwordx2 v151, v[58:59], s[0:1] offset:288
	v_add_u32_e32 v152, 0x18000, v150
	v_pk_mul_f32 v[118:119], v[118:119], v[130:131]
	v_pk_mul_f32 v[120:121], v[120:121], v[130:131]
	v_exp_f32_e32 v118, v118
	v_exp_f32_e32 v119, v119
	v_exp_f32_e32 v120, v120
	v_exp_f32_e32 v121, v121
	v_pk_add_f32 v[118:119], v[118:119], v[132:133]
	v_pk_add_f32 v[120:121], v[120:121], v[132:133]
	v_rcp_f32_e32 v118, v118
	v_rcp_f32_e32 v119, v119
	v_rcp_f32_e32 v120, v120
	v_rcp_f32_e32 v121, v121
	v_cvt_pk_bf16_f32 v118, v118, v119
	v_cvt_pk_bf16_f32 v119, v120, v121
	global_store_dwordx2 v152, v[118:119], s[0:1]
	v_pk_mul_f32 v[114:115], v[114:115], v[130:131]
	v_pk_mul_f32 v[116:117], v[116:117], v[130:131]
	v_exp_f32_e32 v114, v114
	v_exp_f32_e32 v115, v115
	v_exp_f32_e32 v116, v116
	v_exp_f32_e32 v117, v117
	v_pk_add_f32 v[114:115], v[114:115], v[132:133]
	v_pk_add_f32 v[116:117], v[116:117], v[132:133]
	v_rcp_f32_e32 v114, v114
	v_rcp_f32_e32 v115, v115
	v_rcp_f32_e32 v116, v116
	v_rcp_f32_e32 v117, v117
	v_cvt_pk_bf16_f32 v114, v114, v115
	v_cvt_pk_bf16_f32 v115, v116, v117
	global_store_dwordx2 v152, v[114:115], s[0:1] offset:32
	v_pk_mul_f32 v[54:55], v[54:55], v[130:131]
	v_pk_mul_f32 v[56:57], v[56:57], v[130:131]
	v_exp_f32_e32 v54, v54
	v_exp_f32_e32 v55, v55
	v_exp_f32_e32 v56, v56
	v_exp_f32_e32 v57, v57
	v_pk_add_f32 v[54:55], v[54:55], v[132:133]
	v_pk_add_f32 v[56:57], v[56:57], v[132:133]
	v_rcp_f32_e32 v54, v54
	v_rcp_f32_e32 v55, v55
	v_rcp_f32_e32 v56, v56
	v_rcp_f32_e32 v57, v57
	v_cvt_pk_bf16_f32 v54, v54, v55
	v_cvt_pk_bf16_f32 v55, v56, v57
	global_store_dwordx2 v152, v[54:55], s[0:1] offset:256
	v_pk_mul_f32 v[50:51], v[50:51], v[130:131]
	v_pk_mul_f32 v[52:53], v[52:53], v[130:131]
	v_exp_f32_e32 v50, v50
	v_exp_f32_e32 v51, v51
	v_exp_f32_e32 v52, v52
	v_exp_f32_e32 v53, v53
	v_pk_add_f32 v[50:51], v[50:51], v[132:133]
	v_pk_add_f32 v[52:53], v[52:53], v[132:133]
	v_rcp_f32_e32 v50, v50
	v_rcp_f32_e32 v51, v51
	v_rcp_f32_e32 v52, v52
	v_rcp_f32_e32 v53, v53
	v_cvt_pk_bf16_f32 v50, v50, v51
	v_cvt_pk_bf16_f32 v51, v52, v53
	global_store_dwordx2 v152, v[50:51], s[0:1] offset:288
	v_add_u32_e32 v151, 0x30000, v150
	v_pk_mul_f32 v[110:111], v[110:111], v[130:131]
	v_pk_mul_f32 v[112:113], v[112:113], v[130:131]
	v_exp_f32_e32 v110, v110
	v_exp_f32_e32 v111, v111
	v_exp_f32_e32 v112, v112
	v_exp_f32_e32 v113, v113
	v_pk_add_f32 v[110:111], v[110:111], v[132:133]
	v_pk_add_f32 v[112:113], v[112:113], v[132:133]
	v_rcp_f32_e32 v110, v110
	v_rcp_f32_e32 v111, v111
	v_rcp_f32_e32 v112, v112
	v_rcp_f32_e32 v113, v113
	v_cvt_pk_bf16_f32 v110, v110, v111
	v_cvt_pk_bf16_f32 v111, v112, v113
	global_store_dwordx2 v151, v[110:111], s[0:1]
	v_pk_mul_f32 v[106:107], v[106:107], v[130:131]
	v_pk_mul_f32 v[108:109], v[108:109], v[130:131]
	v_exp_f32_e32 v106, v106
	v_exp_f32_e32 v107, v107
	v_exp_f32_e32 v108, v108
	v_exp_f32_e32 v109, v109
	v_pk_add_f32 v[106:107], v[106:107], v[132:133]
	v_pk_add_f32 v[108:109], v[108:109], v[132:133]
	v_rcp_f32_e32 v106, v106
	v_rcp_f32_e32 v107, v107
	v_rcp_f32_e32 v108, v108
	v_rcp_f32_e32 v109, v109
	v_cvt_pk_bf16_f32 v106, v106, v107
	v_cvt_pk_bf16_f32 v107, v108, v109
	global_store_dwordx2 v151, v[106:107], s[0:1] offset:32
	v_pk_mul_f32 v[46:47], v[46:47], v[130:131]
	v_pk_mul_f32 v[48:49], v[48:49], v[130:131]
	v_exp_f32_e32 v46, v46
	v_exp_f32_e32 v47, v47
	v_exp_f32_e32 v48, v48
	v_exp_f32_e32 v49, v49
	v_pk_add_f32 v[46:47], v[46:47], v[132:133]
	v_pk_add_f32 v[48:49], v[48:49], v[132:133]
	v_rcp_f32_e32 v46, v46
	v_rcp_f32_e32 v47, v47
	v_rcp_f32_e32 v48, v48
	v_rcp_f32_e32 v49, v49
	v_cvt_pk_bf16_f32 v46, v46, v47
	v_cvt_pk_bf16_f32 v47, v48, v49
	global_store_dwordx2 v151, v[46:47], s[0:1] offset:256
	v_pk_mul_f32 v[42:43], v[42:43], v[130:131]
	v_pk_mul_f32 v[44:45], v[44:45], v[130:131]
	v_exp_f32_e32 v42, v42
	v_exp_f32_e32 v43, v43
	v_exp_f32_e32 v44, v44
	v_exp_f32_e32 v45, v45
	v_pk_add_f32 v[42:43], v[42:43], v[132:133]
	v_pk_add_f32 v[44:45], v[44:45], v[132:133]
	v_rcp_f32_e32 v42, v42
	v_rcp_f32_e32 v43, v43
	v_rcp_f32_e32 v44, v44
	v_rcp_f32_e32 v45, v45
	v_cvt_pk_bf16_f32 v42, v42, v43
	v_cvt_pk_bf16_f32 v43, v44, v45
	global_store_dwordx2 v151, v[42:43], s[0:1] offset:288
	v_add_u32_e32 v152, 0x48000, v150
	v_pk_mul_f32 v[102:103], v[102:103], v[130:131]
	v_pk_mul_f32 v[104:105], v[104:105], v[130:131]
	v_exp_f32_e32 v102, v102
	v_exp_f32_e32 v103, v103
	v_exp_f32_e32 v104, v104
	v_exp_f32_e32 v105, v105
	v_pk_add_f32 v[102:103], v[102:103], v[132:133]
	v_pk_add_f32 v[104:105], v[104:105], v[132:133]
	v_rcp_f32_e32 v102, v102
	v_rcp_f32_e32 v103, v103
	v_rcp_f32_e32 v104, v104
	v_rcp_f32_e32 v105, v105
	v_cvt_pk_bf16_f32 v102, v102, v103
	v_cvt_pk_bf16_f32 v103, v104, v105
	global_store_dwordx2 v152, v[102:103], s[0:1]
	v_pk_mul_f32 v[98:99], v[98:99], v[130:131]
	v_pk_mul_f32 v[100:101], v[100:101], v[130:131]
	v_exp_f32_e32 v98, v98
	v_exp_f32_e32 v99, v99
	v_exp_f32_e32 v100, v100
	v_exp_f32_e32 v101, v101
	v_pk_add_f32 v[98:99], v[98:99], v[132:133]
	v_pk_add_f32 v[100:101], v[100:101], v[132:133]
	v_rcp_f32_e32 v98, v98
	v_rcp_f32_e32 v99, v99
	v_rcp_f32_e32 v100, v100
	v_rcp_f32_e32 v101, v101
	v_cvt_pk_bf16_f32 v98, v98, v99
	v_cvt_pk_bf16_f32 v99, v100, v101
	global_store_dwordx2 v152, v[98:99], s[0:1] offset:32
	v_pk_mul_f32 v[38:39], v[38:39], v[130:131]
	v_pk_mul_f32 v[40:41], v[40:41], v[130:131]
	v_exp_f32_e32 v38, v38
	v_exp_f32_e32 v39, v39
	v_exp_f32_e32 v40, v40
	v_exp_f32_e32 v41, v41
	v_pk_add_f32 v[38:39], v[38:39], v[132:133]
	v_pk_add_f32 v[40:41], v[40:41], v[132:133]
	v_rcp_f32_e32 v38, v38
	v_rcp_f32_e32 v39, v39
	v_rcp_f32_e32 v40, v40
	v_rcp_f32_e32 v41, v41
	v_cvt_pk_bf16_f32 v38, v38, v39
	v_cvt_pk_bf16_f32 v39, v40, v41
	global_store_dwordx2 v152, v[38:39], s[0:1] offset:256
	v_pk_mul_f32 v[34:35], v[34:35], v[130:131]
	v_pk_mul_f32 v[36:37], v[36:37], v[130:131]
	v_exp_f32_e32 v34, v34
	v_exp_f32_e32 v35, v35
	v_exp_f32_e32 v36, v36
	v_exp_f32_e32 v37, v37
	v_pk_add_f32 v[34:35], v[34:35], v[132:133]
	v_pk_add_f32 v[36:37], v[36:37], v[132:133]
	v_rcp_f32_e32 v34, v34
	v_rcp_f32_e32 v35, v35
	v_rcp_f32_e32 v36, v36
	v_rcp_f32_e32 v37, v37
	v_cvt_pk_bf16_f32 v34, v34, v35
	v_cvt_pk_bf16_f32 v35, v36, v37
	global_store_dwordx2 v152, v[34:35], s[0:1] offset:288
	v_add_u32_e32 v151, 0xc0000, v150
	v_pk_mul_f32 v[94:95], v[94:95], v[130:131]
	v_pk_mul_f32 v[96:97], v[96:97], v[130:131]
	v_exp_f32_e32 v94, v94
	v_exp_f32_e32 v95, v95
	v_exp_f32_e32 v96, v96
	v_exp_f32_e32 v97, v97
	v_pk_add_f32 v[94:95], v[94:95], v[132:133]
	v_pk_add_f32 v[96:97], v[96:97], v[132:133]
	v_rcp_f32_e32 v94, v94
	v_rcp_f32_e32 v95, v95
	v_rcp_f32_e32 v96, v96
	v_rcp_f32_e32 v97, v97
	v_cvt_pk_bf16_f32 v94, v94, v95
	v_cvt_pk_bf16_f32 v95, v96, v97
	global_store_dwordx2 v151, v[94:95], s[0:1]
	v_pk_mul_f32 v[90:91], v[90:91], v[130:131]
	v_pk_mul_f32 v[92:93], v[92:93], v[130:131]
	v_exp_f32_e32 v90, v90
	v_exp_f32_e32 v91, v91
	v_exp_f32_e32 v92, v92
	v_exp_f32_e32 v93, v93
	v_pk_add_f32 v[90:91], v[90:91], v[132:133]
	v_pk_add_f32 v[92:93], v[92:93], v[132:133]
	v_rcp_f32_e32 v90, v90
	v_rcp_f32_e32 v91, v91
	v_rcp_f32_e32 v92, v92
	v_rcp_f32_e32 v93, v93
	v_cvt_pk_bf16_f32 v90, v90, v91
	v_cvt_pk_bf16_f32 v91, v92, v93
	global_store_dwordx2 v151, v[90:91], s[0:1] offset:32
	v_pk_mul_f32 v[30:31], v[30:31], v[130:131]
	v_pk_mul_f32 v[32:33], v[32:33], v[130:131]
	v_exp_f32_e32 v30, v30
	v_exp_f32_e32 v31, v31
	v_exp_f32_e32 v32, v32
	v_exp_f32_e32 v33, v33
	v_pk_add_f32 v[30:31], v[30:31], v[132:133]
	v_pk_add_f32 v[32:33], v[32:33], v[132:133]
	v_rcp_f32_e32 v30, v30
	v_rcp_f32_e32 v31, v31
	v_rcp_f32_e32 v32, v32
	v_rcp_f32_e32 v33, v33
	v_cvt_pk_bf16_f32 v30, v30, v31
	v_cvt_pk_bf16_f32 v31, v32, v33
	global_store_dwordx2 v151, v[30:31], s[0:1] offset:256
	v_pk_mul_f32 v[26:27], v[26:27], v[130:131]
	v_pk_mul_f32 v[28:29], v[28:29], v[130:131]
	v_exp_f32_e32 v26, v26
	v_exp_f32_e32 v27, v27
	v_exp_f32_e32 v28, v28
	v_exp_f32_e32 v29, v29
	v_pk_add_f32 v[26:27], v[26:27], v[132:133]
	v_pk_add_f32 v[28:29], v[28:29], v[132:133]
	v_rcp_f32_e32 v26, v26
	v_rcp_f32_e32 v27, v27
	v_rcp_f32_e32 v28, v28
	v_rcp_f32_e32 v29, v29
	v_cvt_pk_bf16_f32 v26, v26, v27
	v_cvt_pk_bf16_f32 v27, v28, v29
	global_store_dwordx2 v151, v[26:27], s[0:1] offset:288
	v_add_u32_e32 v152, 0xd8000, v150
	v_pk_mul_f32 v[86:87], v[86:87], v[130:131]
	v_pk_mul_f32 v[88:89], v[88:89], v[130:131]
	v_exp_f32_e32 v86, v86
	v_exp_f32_e32 v87, v87
	v_exp_f32_e32 v88, v88
	v_exp_f32_e32 v89, v89
	v_pk_add_f32 v[86:87], v[86:87], v[132:133]
	v_pk_add_f32 v[88:89], v[88:89], v[132:133]
	v_rcp_f32_e32 v86, v86
	v_rcp_f32_e32 v87, v87
	v_rcp_f32_e32 v88, v88
	v_rcp_f32_e32 v89, v89
	v_cvt_pk_bf16_f32 v86, v86, v87
	v_cvt_pk_bf16_f32 v87, v88, v89
	global_store_dwordx2 v152, v[86:87], s[0:1]
	v_pk_mul_f32 v[82:83], v[82:83], v[130:131]
	v_pk_mul_f32 v[84:85], v[84:85], v[130:131]
	v_exp_f32_e32 v82, v82
	v_exp_f32_e32 v83, v83
	v_exp_f32_e32 v84, v84
	v_exp_f32_e32 v85, v85
	v_pk_add_f32 v[82:83], v[82:83], v[132:133]
	v_pk_add_f32 v[84:85], v[84:85], v[132:133]
	v_rcp_f32_e32 v82, v82
	v_rcp_f32_e32 v83, v83
	v_rcp_f32_e32 v84, v84
	v_rcp_f32_e32 v85, v85
	v_cvt_pk_bf16_f32 v82, v82, v83
	v_cvt_pk_bf16_f32 v83, v84, v85
	global_store_dwordx2 v152, v[82:83], s[0:1] offset:32
	v_pk_mul_f32 v[22:23], v[22:23], v[130:131]
	v_pk_mul_f32 v[24:25], v[24:25], v[130:131]
	v_exp_f32_e32 v22, v22
	v_exp_f32_e32 v23, v23
	v_exp_f32_e32 v24, v24
	v_exp_f32_e32 v25, v25
	v_pk_add_f32 v[22:23], v[22:23], v[132:133]
	v_pk_add_f32 v[24:25], v[24:25], v[132:133]
	v_rcp_f32_e32 v22, v22
	v_rcp_f32_e32 v23, v23
	v_rcp_f32_e32 v24, v24
	v_rcp_f32_e32 v25, v25
	v_cvt_pk_bf16_f32 v22, v22, v23
	v_cvt_pk_bf16_f32 v23, v24, v25
	global_store_dwordx2 v152, v[22:23], s[0:1] offset:256
	v_pk_mul_f32 v[18:19], v[18:19], v[130:131]
	v_pk_mul_f32 v[20:21], v[20:21], v[130:131]
	v_exp_f32_e32 v18, v18
	v_exp_f32_e32 v19, v19
	v_exp_f32_e32 v20, v20
	v_exp_f32_e32 v21, v21
	v_pk_add_f32 v[18:19], v[18:19], v[132:133]
	v_pk_add_f32 v[20:21], v[20:21], v[132:133]
	v_rcp_f32_e32 v18, v18
	v_rcp_f32_e32 v19, v19
	v_rcp_f32_e32 v20, v20
	v_rcp_f32_e32 v21, v21
	v_cvt_pk_bf16_f32 v18, v18, v19
	v_cvt_pk_bf16_f32 v19, v20, v21
	global_store_dwordx2 v152, v[18:19], s[0:1] offset:288
	v_add_u32_e32 v151, 0xf0000, v150
	v_pk_mul_f32 v[78:79], v[78:79], v[130:131]
	v_pk_mul_f32 v[80:81], v[80:81], v[130:131]
	v_exp_f32_e32 v78, v78
	v_exp_f32_e32 v79, v79
	v_exp_f32_e32 v80, v80
	v_exp_f32_e32 v81, v81
	v_pk_add_f32 v[78:79], v[78:79], v[132:133]
	v_pk_add_f32 v[80:81], v[80:81], v[132:133]
	v_rcp_f32_e32 v78, v78
	v_rcp_f32_e32 v79, v79
	v_rcp_f32_e32 v80, v80
	v_rcp_f32_e32 v81, v81
	v_cvt_pk_bf16_f32 v78, v78, v79
	v_cvt_pk_bf16_f32 v79, v80, v81
	global_store_dwordx2 v151, v[78:79], s[0:1]
	v_pk_mul_f32 v[74:75], v[74:75], v[130:131]
	v_pk_mul_f32 v[76:77], v[76:77], v[130:131]
	v_exp_f32_e32 v74, v74
	v_exp_f32_e32 v75, v75
	v_exp_f32_e32 v76, v76
	v_exp_f32_e32 v77, v77
	v_pk_add_f32 v[74:75], v[74:75], v[132:133]
	v_pk_add_f32 v[76:77], v[76:77], v[132:133]
	v_rcp_f32_e32 v74, v74
	v_rcp_f32_e32 v75, v75
	v_rcp_f32_e32 v76, v76
	v_rcp_f32_e32 v77, v77
	v_cvt_pk_bf16_f32 v74, v74, v75
	v_cvt_pk_bf16_f32 v75, v76, v77
	global_store_dwordx2 v151, v[74:75], s[0:1] offset:32
	v_pk_mul_f32 v[14:15], v[14:15], v[130:131]
	v_pk_mul_f32 v[16:17], v[16:17], v[130:131]
	v_exp_f32_e32 v14, v14
	v_exp_f32_e32 v15, v15
	v_exp_f32_e32 v16, v16
	v_exp_f32_e32 v17, v17
	v_pk_add_f32 v[14:15], v[14:15], v[132:133]
	v_pk_add_f32 v[16:17], v[16:17], v[132:133]
	v_rcp_f32_e32 v14, v14
	v_rcp_f32_e32 v15, v15
	v_rcp_f32_e32 v16, v16
	v_rcp_f32_e32 v17, v17
	v_cvt_pk_bf16_f32 v14, v14, v15
	v_cvt_pk_bf16_f32 v15, v16, v17
	global_store_dwordx2 v151, v[14:15], s[0:1] offset:256
	v_pk_mul_f32 v[10:11], v[10:11], v[130:131]
	v_pk_mul_f32 v[12:13], v[12:13], v[130:131]
	v_exp_f32_e32 v10, v10
	v_exp_f32_e32 v11, v11
	v_exp_f32_e32 v12, v12
	v_exp_f32_e32 v13, v13
	v_pk_add_f32 v[10:11], v[10:11], v[132:133]
	v_pk_add_f32 v[12:13], v[12:13], v[132:133]
	v_rcp_f32_e32 v10, v10
	v_rcp_f32_e32 v11, v11
	v_rcp_f32_e32 v12, v12
	v_rcp_f32_e32 v13, v13
	v_cvt_pk_bf16_f32 v10, v10, v11
	v_cvt_pk_bf16_f32 v11, v12, v13
	global_store_dwordx2 v151, v[10:11], s[0:1] offset:288
	v_add_u32_e32 v152, 0x108000, v150
	v_pk_mul_f32 v[70:71], v[70:71], v[130:131]
	v_pk_mul_f32 v[72:73], v[72:73], v[130:131]
	v_exp_f32_e32 v70, v70
	v_exp_f32_e32 v71, v71
	v_exp_f32_e32 v72, v72
	v_exp_f32_e32 v73, v73
	v_pk_add_f32 v[70:71], v[70:71], v[132:133]
	v_pk_add_f32 v[72:73], v[72:73], v[132:133]
	v_rcp_f32_e32 v70, v70
	v_rcp_f32_e32 v71, v71
	v_rcp_f32_e32 v72, v72
	v_rcp_f32_e32 v73, v73
	v_cvt_pk_bf16_f32 v70, v70, v71
	v_cvt_pk_bf16_f32 v71, v72, v73
	global_store_dwordx2 v152, v[70:71], s[0:1]
	v_pk_mul_f32 v[66:67], v[66:67], v[130:131]
	v_pk_mul_f32 v[68:69], v[68:69], v[130:131]
	v_exp_f32_e32 v66, v66
	v_exp_f32_e32 v67, v67
	v_exp_f32_e32 v68, v68
	v_exp_f32_e32 v69, v69
	v_pk_add_f32 v[66:67], v[66:67], v[132:133]
	v_pk_add_f32 v[68:69], v[68:69], v[132:133]
	v_rcp_f32_e32 v66, v66
	v_rcp_f32_e32 v67, v67
	v_rcp_f32_e32 v68, v68
	v_rcp_f32_e32 v69, v69
	v_cvt_pk_bf16_f32 v66, v66, v67
	v_cvt_pk_bf16_f32 v67, v68, v69
	global_store_dwordx2 v152, v[66:67], s[0:1] offset:32
	v_pk_mul_f32 v[6:7], v[6:7], v[130:131]
	v_pk_mul_f32 v[8:9], v[8:9], v[130:131]
	v_exp_f32_e32 v6, v6
	v_exp_f32_e32 v7, v7
	v_exp_f32_e32 v8, v8
	v_exp_f32_e32 v9, v9
	v_pk_add_f32 v[6:7], v[6:7], v[132:133]
	v_pk_add_f32 v[8:9], v[8:9], v[132:133]
	v_rcp_f32_e32 v6, v6
	v_rcp_f32_e32 v7, v7
	v_rcp_f32_e32 v8, v8
	v_rcp_f32_e32 v9, v9
	v_cvt_pk_bf16_f32 v6, v6, v7
	v_cvt_pk_bf16_f32 v7, v8, v9
	global_store_dwordx2 v152, v[6:7], s[0:1] offset:256
	v_pk_mul_f32 v[2:3], v[2:3], v[130:131]
	v_pk_mul_f32 v[4:5], v[4:5], v[130:131]
	v_exp_f32_e32 v2, v2
	v_exp_f32_e32 v3, v3
	v_exp_f32_e32 v4, v4
	v_exp_f32_e32 v5, v5
	v_pk_add_f32 v[2:3], v[2:3], v[132:133]
	v_pk_add_f32 v[4:5], v[4:5], v[132:133]
	v_rcp_f32_e32 v2, v2
	v_rcp_f32_e32 v3, v3
	v_rcp_f32_e32 v4, v4
	v_rcp_f32_e32 v5, v5
	v_cvt_pk_bf16_f32 v2, v2, v3
	v_cvt_pk_bf16_f32 v3, v4, v5
	global_store_dwordx2 v152, v[2:3], s[0:1] offset:288
	s_branch .LBB0_1023
.Lg0_orig:
	s_lshl_b32 s71, s42, 8
	s_cmp_gt_i32 s42, 2
	s_cselect_b64 s[38:39], -1, 0
	s_cmpk_gt_u32 s71, 0x3ff
	s_cselect_b64 s[42:43], -1, 0
	s_cmpk_gt_u32 s71, 0x5ff
	v_add_u32_e32 v130, s24, v143
	s_cselect_b64 s[24:25], -1, 0
	s_cmpk_gt_u32 s71, 0x6ff
	s_cselect_b64 s[20:21], -1, 0
	s_cmpk_gt_u32 s71, 0x67f
	s_cselect_b64 s[0:1], -1, 0
	s_and_b64 s[0:1], s[0:1], exec
	s_movk_i32 s0, 0xf980
	s_cselect_b32 s86, s0, 0xfffffa00
	s_mov_b32 s0, 0xb240000
	s_cselect_b32 s26, s0, 0xae40000
	s_mov_b32 s0, 0xe00000
	v_ashrrev_i32_e32 v0, 6, v130
	s_cselect_b32 s84, s0, 0xc00000
	v_and_b32_e32 v0, -4, v0
	v_readlane_b32 s0, v249, 47
	v_readlane_b32 s1, v249, 48
	v_ashrrev_i32_e32 v131, 31, v130
	v_add_u32_e32 v132, s0, v0
	s_movk_i32 s0, 0x1800
	v_mad_i64_i32 v[156:157], s[0:1], v130, s0, 0
	s_movk_i32 s0, 0x1000
	v_ashrrev_i32_e32 v133, 31, v132
	v_cmp_gt_i32_e64 s[40:41], s0, v130
	s_movk_i32 s0, 0xfff
	v_add_u32_e32 v0, 0xfffff000, v130
	v_or_b32_e32 v160, s71, v218
	v_lshlrev_b64 v[132:133], 17, v[132:133]
	v_cmp_lt_i32_e64 s[0:1], s0, v130
	v_lshlrev_b64 v[154:155], 9, v[0:1]
	v_lshlrev_b64 v[152:153], 11, v[130:131]
	v_lshlrev_b64 v[150:151], 10, v[130:131]
	s_mov_b64 s[44:45], -1
	s_and_b64 vcc, exec, s[38:39]
	s_cbranch_vccz .LBB0_1298
	s_and_b64 vcc, exec, s[42:43]
	s_cbranch_vccz .LBB0_1295
	s_and_b64 vcc, exec, s[24:25]
	s_cbranch_vccz .LBB0_1292
	s_and_b64 vcc, exec, s[20:21]
	s_cbranch_vccz .LBB0_1285
	v_mul_f32_e32 v159, 0xbfb8aa3b, v128
	v_mul_f32_e32 v161, 0xbfb8aa3b, v129
	v_exp_f32_e32 v159, v159
	v_exp_f32_e32 v161, v161
	v_mul_f32_e32 v0, 0xbfb8aa3b, v126
	v_mul_f32_e32 v158, 0xbfb8aa3b, v127
	v_exp_f32_e32 v0, v0
	v_exp_f32_e32 v158, v158
	v_add_f32_e32 v159, 1.0, v159
	v_add_f32_e32 v161, 1.0, v161
	v_rcp_f32_e32 v159, v159
	v_rcp_f32_e32 v161, v161
	v_add_f32_e32 v0, 1.0, v0
	v_add_f32_e32 v158, 1.0, v158
	v_rcp_f32_e32 v0, v0
	v_rcp_f32_e32 v158, v158
	v_cvt_pk_bf16_f32 v159, v159, v161
	v_lshl_add_u64 v[162:163], s[94:95], 0, v[156:157]
	v_mov_b32_e32 v161, v1
	v_lshl_add_u64 v[162:163], v[160:161], 1, v[162:163]
	v_add_co_u32_e32 v162, vcc, 0xb63f000, v162
	v_cvt_pk_bf16_f32 v158, v0, v158
	s_nop 0
	v_addc_co_u32_e32 v163, vcc, 0, v163, vcc
	global_store_dwordx2 v[162:163], v[158:159], off offset:512
	s_mov_b64 s[44:45], 0
